# combined: dword mixer stores + LDS-DMA pool staging + DPP reductions + K-loop no-op trim + static prio for waves 4-7, on the non-GEMM latency stack
# baseline (speedup 1.0000x reference)
; #define PG8_STAGE(bufoff, gbase, voff) do { glds_s((const char*)(gbase), (voff), ldsb + (bufoff)); glds_s((const char*)(gbase) + rstep, (voff), ldsb + (bufoff) + 8192u); } while (0)
; #define PG8_LDA(dst, b, h) do { _Pragma("unroll") for (int m = 0; m < 4; ++m) _Pragma("unroll") for (int k = 0; k < 2; ++k) dst[m][k] = *(const LAS bf16x8*)(lds + PG8_SA(b, h) + aoff + m * 2048 + k * 1024); } while (0)
; #define PG8_LDB(dst, b, h) do { _Pragma("unroll") for (int n = 0; n < 2; ++n) _Pragma("unroll") for (int k = 0; k < 2; ++k) dst[n][k] = *(const LAS bf16x8*)(lds + PG8_SB(b, h) + boff + n * 2048 + k * 1024); } while (0)
; #define PG8_MMA(ai, bj, At, Bt) do { __builtin_amdgcn_s_setprio(1); _Pragma("unroll") for (int m = 0; m < 4; ++m) _Pragma("unroll") for (int n = 0; n < 2; ++n) _Pragma("unroll") for (int k = 0; k < 2; ++k) \
;         acc[ai][bj][m][n] = __builtin_amdgcn_mfma_f32_16x16x32_bf16(Bt[n][k], At[m][k], acc[ai][bj][m][n], 0, 0, 0); __builtin_amdgcn_s_setprio(0); } while (0)
; #define PG8_WAIT_V(n) asm volatile("s_waitcnt vmcnt(" #n ")" ::: "memory")
; #define PG8_WAIT_L(n) asm volatile("s_waitcnt lgkmcnt(" #n ")" ::: "memory")
; #define PG8_BAR __builtin_amdgcn_s_barrier()
; #define PG8_SCHED __builtin_amdgcn_sched_barrier(0)
; template <class Epi, class Sched>
; __device__ __forceinline__ void gemm_phase(LAS unsigned char* lds, const Gemm g, const Sched& S, const Epi& E, const int tid) {
;     ...
;             PG8_LDB(B0, 0, 0); PG8_LDB(B1, 0, 1); PG8_SCHED; PG8_LDA(At, 0, 0); if (!relax) PG8_STAGE(PG8_SA(1, 1), a1 + hstep, voffA);
;             if (relax) PG8_WAIT_V(16); else PG8_WAIT_V(8);
;             PG8_WAIT_L(0); PG8_BAR; PG8_MMA(0, 0, At, B0); PG8_MMA(0, 1, At, B1); PG8_BAR; PG8_SCHED;
;             PG8_LDA(At, 0, 1); PG8_STAGE(PG8_SB(0, 0), b2, voffB); PG8_STAGE(PG8_SB(0, 1), b2 + hstep, voffB); PG8_STAGE(PG8_SA(0, 0), a2, voffA);
;             if (relax) PG8_WAIT_V(16); else PG8_WAIT_V(8);
.LBB0_193:
	s_add_u32 s8, s2, 0x100
	s_waitcnt lgkmcnt(0)
	s_addc_u32 s9, s3, 0
	s_add_u32 s44, s0, 0x100
	s_addc_u32 s45, s1, 0
	s_barrier
	v_mfma_f32_16x16x32_bf16 v[0:3], v[80:83], v[36:39], 0
	v_mfma_f32_16x16x32_bf16 v[4:7], v[88:91], v[36:39], 0
	v_mfma_f32_16x16x32_bf16 v[8:11], v[80:83], v[44:47], 0
	v_mfma_f32_16x16x32_bf16 v[12:15], v[88:91], v[44:47], 0
	v_mfma_f32_16x16x32_bf16 v[16:19], v[80:83], v[52:55], 0
	v_mfma_f32_16x16x32_bf16 v[20:23], v[88:91], v[52:55], 0
	v_mfma_f32_16x16x32_bf16 v[24:27], v[80:83], v[60:63], 0
	v_mfma_f32_16x16x32_bf16 v[28:31], v[88:91], v[60:63], 0
	v_mfma_f32_16x16x32_bf16 v[0:3], v[84:87], v[40:43], v[0:3]
	v_mfma_f32_16x16x32_bf16 v[4:7], v[92:95], v[40:43], v[4:7]
	v_mfma_f32_16x16x32_bf16 v[8:11], v[84:87], v[48:51], v[8:11]
	v_mfma_f32_16x16x32_bf16 v[12:15], v[92:95], v[48:51], v[12:15]
	v_mfma_f32_16x16x32_bf16 v[16:19], v[84:87], v[56:59], v[16:19]
	v_mfma_f32_16x16x32_bf16 v[20:23], v[92:95], v[56:59], v[20:23]
	v_mfma_f32_16x16x32_bf16 v[24:27], v[84:87], v[96:99], v[24:27]
	v_mfma_f32_16x16x32_bf16 v[28:31], v[92:95], v[96:99], v[28:31]
	v_mfma_f32_16x16x32_bf16 v[32:35], v[64:67], v[36:39], 0
	v_mfma_f32_16x16x32_bf16 v[36:39], v[72:75], v[36:39], 0
	v_mfma_f32_16x16x32_bf16 v[32:35], v[68:71], v[40:43], v[32:35]
	v_mfma_f32_16x16x32_bf16 v[36:39], v[76:79], v[40:43], v[36:39]
	v_mfma_f32_16x16x32_bf16 v[40:43], v[64:67], v[44:47], 0
	v_mfma_f32_16x16x32_bf16 v[44:47], v[72:75], v[44:47], 0
	v_mfma_f32_16x16x32_bf16 v[40:43], v[68:71], v[48:51], v[40:43]
	v_mfma_f32_16x16x32_bf16 v[44:47], v[76:79], v[48:51], v[44:47]
	v_mfma_f32_16x16x32_bf16 v[48:51], v[64:67], v[52:55], 0
	v_mfma_f32_16x16x32_bf16 v[52:55], v[72:75], v[52:55], 0
	v_mfma_f32_16x16x32_bf16 v[48:51], v[68:71], v[56:59], v[48:51]
	v_mfma_f32_16x16x32_bf16 v[52:55], v[76:79], v[56:59], v[52:55]
	v_mfma_f32_16x16x32_bf16 v[56:59], v[64:67], v[60:63], 0
	v_mfma_f32_16x16x32_bf16 v[60:63], v[72:75], v[60:63], 0
	v_mfma_f32_16x16x32_bf16 v[56:59], v[68:71], v[96:99], v[56:59]
	v_mfma_f32_16x16x32_bf16 v[60:63], v[76:79], v[96:99], v[60:63]
	s_barrier
	ds_read_b128 v[120:123], v250 offset:16384
	s_waitcnt vmcnt(35)
	ds_read_b128 v[124:127], v250 offset:17408
	ds_read_b128 v[112:115], v250 offset:18432
	ds_read_b128 v[116:119], v250 offset:19456
	ds_read_b128 v[104:107], v250 offset:20480
	ds_read_b128 v[108:111], v250 offset:21504
	ds_read_b128 v[96:99], v250 offset:22528
	ds_read_b128 v[100:103], v250 offset:23552
	s_mov_b32 m0, s50
	s_nop 0
	global_load_lds_dwordx4 v246, s[44:45]
	s_add_u32 s44, s44, s28
	s_addc_u32 s45, s45, s29
	s_add_u32 s85, s0, s30
	s_addc_u32 s96, s1, s31
	s_mov_b32 m0, s51
	s_nop 0
	global_load_lds_dwordx4 v246, s[44:45]
	s_add_u32 s44, s85, 0x100
	s_addc_u32 s45, s96, 0
	s_mov_b32 m0, s52
	s_nop 0
	global_load_lds_dwordx4 v246, s[44:45]
	s_add_u32 s44, s44, s28
	s_addc_u32 s45, s45, s29
	s_mov_b32 m0, s53
	s_nop 0
	global_load_lds_dwordx4 v246, s[44:45]
	s_nop 0
	s_mov_b32 m0, s49
	s_nop 0
	global_load_lds_dwordx4 v245, s[8:9]
	s_add_u32 s8, s8, s28
	s_addc_u32 s9, s9, s29
	s_mov_b32 m0, s54
	s_nop 0
	global_load_lds_dwordx4 v245, s[8:9]
	s_and_b64 vcc, exec, s[6:7]
	s_cbranch_vccz .LBB0_215
	s_waitcnt vmcnt(16)
	s_cbranch_execnz .LBB0_196

; #define PG8_STAGE(bufoff, gbase, voff) do { glds_s((const char*)(gbase), (voff), ldsb + (bufoff)); glds_s((const char*)(gbase) + rstep, (voff), ldsb + (bufoff) + 8192u); } while (0)
; #define PG8_LDA(dst, b, h) do { _Pragma("unroll") for (int m = 0; m < 4; ++m) _Pragma("unroll") for (int k = 0; k < 2; ++k) dst[m][k] = *(const LAS bf16x8*)(lds + PG8_SA(b, h) + aoff + m * 2048 + k * 1024); } while (0)
; #define PG8_LDB(dst, b, h) do { _Pragma("unroll") for (int n = 0; n < 2; ++n) _Pragma("unroll") for (int k = 0; k < 2; ++k) dst[n][k] = *(const LAS bf16x8*)(lds + PG8_SB(b, h) + boff + n * 2048 + k * 1024); } while (0)
; #define PG8_MMA(ai, bj, At, Bt) do { __builtin_amdgcn_s_setprio(1); _Pragma("unroll") for (int m = 0; m < 4; ++m) _Pragma("unroll") for (int n = 0; n < 2; ++n) _Pragma("unroll") for (int k = 0; k < 2; ++k) \
;         acc[ai][bj][m][n] = __builtin_amdgcn_mfma_f32_16x16x32_bf16(Bt[n][k], At[m][k], acc[ai][bj][m][n], 0, 0, 0); __builtin_amdgcn_s_setprio(0); } while (0)
; #define PG8_WAIT_V(n) asm volatile("s_waitcnt vmcnt(" #n ")" ::: "memory")
; #define PG8_WAIT_L(n) asm volatile("s_waitcnt lgkmcnt(" #n ")" ::: "memory")
; #define PG8_BAR __builtin_amdgcn_s_barrier()
; #define PG8_SCHED __builtin_amdgcn_sched_barrier(0)
; template <class Epi, class Sched>
; __device__ __forceinline__ void gemm_phase(LAS unsigned char* lds, const Gemm g, const Sched& S, const Epi& E, const int tid) {
;     ...
;             PG8_WAIT_L(0); PG8_BAR; PG8_MMA(1, 0, At, B0); PG8_MMA(1, 1, At, B1); PG8_BAR; PG8_SCHED;
;             PG8_LDB(B0, 1, 0); PG8_LDB(B1, 1, 1); PG8_SCHED; PG8_LDA(At, 1, 0); PG8_STAGE(PG8_SA(0, 1), a2 + hstep, voffA);
;             if (relax) PG8_WAIT_V(16); else PG8_WAIT_V(8);
.LBB0_196:
	s_waitcnt lgkmcnt(0)
	s_barrier
	s_waitcnt vmcnt(34) lgkmcnt(7)
	v_mfma_f32_16x16x32_bf16 v[128:131], v[80:83], v[120:123], 0
	v_mfma_f32_16x16x32_bf16 v[150:153], v[84:87], v[124:127], v[128:131]
	v_mfma_f32_16x16x32_bf16 v[128:131], v[88:91], v[120:123], 0
	v_mfma_f32_16x16x32_bf16 v[154:157], v[92:95], v[124:127], v[128:131]
	v_mfma_f32_16x16x32_bf16 v[128:131], v[80:83], v[112:115], 0
	v_mfma_f32_16x16x32_bf16 v[158:161], v[84:87], v[116:119], v[128:131]
	v_mfma_f32_16x16x32_bf16 v[128:131], v[88:91], v[112:115], 0
	v_mfma_f32_16x16x32_bf16 v[162:165], v[92:95], v[116:119], v[128:131]
	v_mfma_f32_16x16x32_bf16 v[128:131], v[80:83], v[104:107], 0
	v_mfma_f32_16x16x32_bf16 v[80:83], v[80:83], v[96:99], 0
	v_mfma_f32_16x16x32_bf16 v[166:169], v[84:87], v[108:111], v[128:131]
	v_mfma_f32_16x16x32_bf16 v[128:131], v[88:91], v[104:107], 0
	v_mfma_f32_16x16x32_bf16 v[174:177], v[84:87], v[100:103], v[80:83]
	v_mfma_f32_16x16x32_bf16 v[80:83], v[88:91], v[96:99], 0
	v_mfma_f32_16x16x32_bf16 v[170:173], v[92:95], v[108:111], v[128:131]
	v_mfma_f32_16x16x32_bf16 v[86:89], v[92:95], v[100:103], v[80:83]
	v_mfma_f32_16x16x32_bf16 v[80:83], v[64:67], v[120:123], 0
	v_mfma_f32_16x16x32_bf16 v[178:181], v[68:71], v[124:127], v[80:83]
	v_mfma_f32_16x16x32_bf16 v[80:83], v[72:75], v[120:123], 0
	v_mfma_f32_16x16x32_bf16 v[182:185], v[76:79], v[124:127], v[80:83]
	v_mfma_f32_16x16x32_bf16 v[80:83], v[64:67], v[112:115], 0
	v_mfma_f32_16x16x32_bf16 v[186:189], v[68:71], v[116:119], v[80:83]
	v_mfma_f32_16x16x32_bf16 v[80:83], v[72:75], v[112:115], 0
	v_mfma_f32_16x16x32_bf16 v[190:193], v[76:79], v[116:119], v[80:83]
	v_mfma_f32_16x16x32_bf16 v[80:83], v[64:67], v[104:107], 0
	v_mfma_f32_16x16x32_bf16 v[64:67], v[64:67], v[96:99], 0
	v_mfma_f32_16x16x32_bf16 v[194:197], v[68:71], v[108:111], v[80:83]
	v_mfma_f32_16x16x32_bf16 v[80:83], v[72:75], v[104:107], 0
	v_mfma_f32_16x16x32_bf16 v[202:205], v[68:71], v[100:103], v[64:67]
	v_mfma_f32_16x16x32_bf16 v[64:67], v[72:75], v[96:99], 0
	v_mfma_f32_16x16x32_bf16 v[198:201], v[76:79], v[108:111], v[80:83]
	v_mfma_f32_16x16x32_bf16 v[206:209], v[76:79], v[100:103], v[64:67]
	s_barrier
	v_add_u32_e32 v252, 0x18000, v249
	v_add_u32_e32 v240, 0x1c000, v249
	s_nop 1
	ds_read_b128 v[66:69], v252
	ds_read_b128 v[74:77], v252 offset:1024
	ds_read_b128 v[226:229], v252 offset:2048
	ds_read_b128 v[230:233], v252 offset:3072
	ds_read_b128 v[210:213], v240
	ds_read_b128 v[214:217], v240 offset:1024
	ds_read_b128 v[218:221], v240 offset:2048
	ds_read_b128 v[222:225], v240 offset:3072
	ds_read_b128 v[122:125], v250 offset:32768
	s_waitcnt vmcnt(33)
	ds_read_b128 v[130:133], v250 offset:33792
	ds_read_b128 v[106:109], v250 offset:34816
	ds_read_b128 v[114:117], v250 offset:35840
	ds_read_b128 v[90:93], v250 offset:36864
	ds_read_b128 v[98:101], v250 offset:37888
	ds_read_b128 v[70:73], v250 offset:38912
	ds_read_b128 v[78:81], v250 offset:39936
	s_add_u32 s8, s40, 0x100
	s_addc_u32 s9, s41, 0
	s_mov_b32 m0, s55
	s_nop 0
	global_load_lds_dwordx4 v245, s[8:9]
	s_add_u32 s8, s8, s28
	s_addc_u32 s9, s9, s29
	s_mov_b32 m0, s56
	s_nop 0
	global_load_lds_dwordx4 v245, s[8:9]
	s_and_b64 vcc, exec, s[6:7]
	s_cbranch_vccz .LBB0_216
	s_waitcnt vmcnt(16)
	s_cbranch_execnz .LBB0_199

; #define PG8_STAGE(bufoff, gbase, voff) do { glds_s((const char*)(gbase), (voff), ldsb + (bufoff)); glds_s((const char*)(gbase) + rstep, (voff), ldsb + (bufoff) + 8192u); } while (0)
; #define PG8_LDA(dst, b, h) do { _Pragma("unroll") for (int m = 0; m < 4; ++m) _Pragma("unroll") for (int k = 0; k < 2; ++k) dst[m][k] = *(const LAS bf16x8*)(lds + PG8_SA(b, h) + aoff + m * 2048 + k * 1024); } while (0)
; #define PG8_MMA(ai, bj, At, Bt) do { __builtin_amdgcn_s_setprio(1); _Pragma("unroll") for (int m = 0; m < 4; ++m) _Pragma("unroll") for (int n = 0; n < 2; ++n) _Pragma("unroll") for (int k = 0; k < 2; ++k) \
;         acc[ai][bj][m][n] = __builtin_amdgcn_mfma_f32_16x16x32_bf16(Bt[n][k], At[m][k], acc[ai][bj][m][n], 0, 0, 0); __builtin_amdgcn_s_setprio(0); } while (0)
; #define PG8_WAIT_V(n) asm volatile("s_waitcnt vmcnt(" #n ")" ::: "memory")
; #define PG8_WAIT_L(n) asm volatile("s_waitcnt lgkmcnt(" #n ")" ::: "memory")
; #define PG8_BAR __builtin_amdgcn_s_barrier()
; #define PG8_SCHED __builtin_amdgcn_sched_barrier(0)
; template <class Epi, class Sched>
; __device__ __forceinline__ void gemm_phase(LAS unsigned char* lds, const Gemm g, const Sched& S, const Epi& E, const int tid) {
;     ...
;             PG8_WAIT_L(0); PG8_BAR; PG8_MMA(0, 0, At, B0); PG8_MMA(0, 1, At, B1); PG8_BAR; PG8_SCHED;
;             PG8_LDA(At, 1, 1); PG8_STAGE(PG8_SB(1, 0), b3, voffB); PG8_STAGE(PG8_SB(1, 1), b3 + hstep, voffB); PG8_STAGE(PG8_SA(1, 0), a3, voffA);
;             PG8_WAIT_V(8); PG8_WAIT_L(0); PG8_BAR; PG8_MMA(1, 0, At, B0); PG8_MMA(1, 1, At, B1); PG8_BAR; PG8_SCHED;
.LBB0_199:
	s_add_u32 s2, s2, 0x180
	s_waitcnt lgkmcnt(0)
	s_addc_u32 s3, s3, 0
	s_add_u32 s6, s0, 0x180
	s_addc_u32 s7, s1, 0
	s_barrier
	v_mfma_f32_16x16x32_bf16 v[0:3], v[66:69], v[122:125], v[0:3]
	v_mfma_f32_16x16x32_bf16 v[142:145], v[74:77], v[130:133], v[0:3]
	v_mfma_f32_16x16x32_bf16 v[0:3], v[226:229], v[122:125], v[4:7]
	s_waitcnt vmcnt(32)
	v_mfma_f32_16x16x32_bf16 v[134:137], v[230:233], v[130:133], v[0:3]
	v_mfma_f32_16x16x32_bf16 v[0:3], v[66:69], v[106:109], v[8:11]
	v_mfma_f32_16x16x32_bf16 v[126:129], v[74:77], v[114:117], v[0:3]
	v_mfma_f32_16x16x32_bf16 v[0:3], v[226:229], v[106:109], v[12:15]
	v_mfma_f32_16x16x32_bf16 v[118:121], v[230:233], v[114:117], v[0:3]
	v_mfma_f32_16x16x32_bf16 v[0:3], v[66:69], v[90:93], v[16:19]
	v_mfma_f32_16x16x32_bf16 v[110:113], v[74:77], v[98:101], v[0:3]
	v_mfma_f32_16x16x32_bf16 v[0:3], v[226:229], v[90:93], v[20:23]
	v_mfma_f32_16x16x32_bf16 v[102:105], v[230:233], v[98:101], v[0:3]
	v_mfma_f32_16x16x32_bf16 v[0:3], v[66:69], v[70:73], v[24:27]
	v_mfma_f32_16x16x32_bf16 v[94:97], v[74:77], v[78:81], v[0:3]
	v_mfma_f32_16x16x32_bf16 v[0:3], v[226:229], v[70:73], v[28:31]
	v_mfma_f32_16x16x32_bf16 v[82:85], v[230:233], v[78:81], v[0:3]
	v_mfma_f32_16x16x32_bf16 v[0:3], v[210:213], v[122:125], v[32:35]
	v_mfma_f32_16x16x32_bf16 v[146:149], v[214:217], v[130:133], v[0:3]
	v_mfma_f32_16x16x32_bf16 v[0:3], v[218:221], v[122:125], v[36:39]
	v_mfma_f32_16x16x32_bf16 v[138:141], v[222:225], v[130:133], v[0:3]
	v_mfma_f32_16x16x32_bf16 v[0:3], v[210:213], v[106:109], v[40:43]
	v_mfma_f32_16x16x32_bf16 v[130:133], v[214:217], v[114:117], v[0:3]
	v_mfma_f32_16x16x32_bf16 v[0:3], v[218:221], v[106:109], v[44:47]
	v_mfma_f32_16x16x32_bf16 v[122:125], v[222:225], v[114:117], v[0:3]
	v_mfma_f32_16x16x32_bf16 v[0:3], v[210:213], v[90:93], v[48:51]
	v_mfma_f32_16x16x32_bf16 v[114:117], v[214:217], v[98:101], v[0:3]
	v_mfma_f32_16x16x32_bf16 v[0:3], v[218:221], v[90:93], v[52:55]
	v_mfma_f32_16x16x32_bf16 v[106:109], v[222:225], v[98:101], v[0:3]
	v_mfma_f32_16x16x32_bf16 v[0:3], v[210:213], v[70:73], v[56:59]
	v_mfma_f32_16x16x32_bf16 v[98:101], v[214:217], v[78:81], v[0:3]
	v_mfma_f32_16x16x32_bf16 v[0:3], v[218:221], v[70:73], v[60:63]
	v_mfma_f32_16x16x32_bf16 v[90:93], v[222:225], v[78:81], v[0:3]
	s_barrier
	s_nop 4
	ds_read_b128 v[0:3], v250 offset:49152
	ds_read_b128 v[4:7], v250 offset:50176
	ds_read_b128 v[8:11], v250 offset:51200
	ds_read_b128 v[12:15], v250 offset:52224
	ds_read_b128 v[16:19], v250 offset:53248
	ds_read_b128 v[26:29], v250 offset:54272
	ds_read_b128 v[236:239], v250 offset:55296
	ds_read_b128 v[20:23], v250 offset:56320
	s_mov_b32 m0, s59
	s_nop 0
	global_load_lds_dwordx4 v246, s[6:7]
	s_add_u32 s6, s6, s28
	s_addc_u32 s7, s7, s29
	s_mov_b32 m0, s60
	s_nop 0
	global_load_lds_dwordx4 v246, s[6:7]
	s_add_u32 s6, s85, 0x180
	s_addc_u32 s7, s96, 0
	s_mov_b32 m0, s63
	s_nop 0
	global_load_lds_dwordx4 v246, s[6:7]
	s_add_u32 s6, s6, s28
	s_addc_u32 s7, s7, s29
	s_mov_b32 m0, s64
	s_nop 0
	global_load_lds_dwordx4 v246, s[6:7]
	s_mov_b32 m0, s61
	s_nop 0
	global_load_lds_dwordx4 v245, s[2:3]
	s_add_u32 s6, s2, s28
	s_addc_u32 s7, s3, s29
	s_mov_b32 m0, s62
	s_nop 0
	global_load_lds_dwordx4 v245, s[6:7]
	s_waitcnt vmcnt(8)
	s_waitcnt lgkmcnt(0)
	s_barrier
	v_mfma_f32_16x16x32_bf16 v[30:33], v[66:69], v[0:3], v[150:153]
	v_mfma_f32_16x16x32_bf16 v[78:81], v[74:77], v[4:7], v[30:33]
	v_mfma_f32_16x16x32_bf16 v[30:33], v[226:229], v[0:3], v[154:157]
	v_mfma_f32_16x16x32_bf16 v[70:73], v[230:233], v[4:7], v[30:33]
	v_mfma_f32_16x16x32_bf16 v[30:33], v[66:69], v[8:11], v[158:161]
	v_mfma_f32_16x16x32_bf16 v[62:65], v[74:77], v[12:15], v[30:33]
	v_mfma_f32_16x16x32_bf16 v[30:33], v[226:229], v[8:11], v[162:165]
	v_mfma_f32_16x16x32_bf16 v[54:57], v[230:233], v[12:15], v[30:33]
	v_mfma_f32_16x16x32_bf16 v[30:33], v[66:69], v[16:19], v[166:169]
	v_mfma_f32_16x16x32_bf16 v[46:49], v[74:77], v[26:29], v[30:33]
	v_mfma_f32_16x16x32_bf16 v[30:33], v[226:229], v[16:19], v[170:173]
	v_mfma_f32_16x16x32_bf16 v[38:41], v[230:233], v[26:29], v[30:33]
	v_mfma_f32_16x16x32_bf16 v[30:33], v[66:69], v[236:239], v[174:177]
	v_mfma_f32_16x16x32_bf16 v[34:37], v[226:229], v[236:239], v[86:89]
	v_mfma_f32_16x16x32_bf16 v[30:33], v[74:77], v[20:23], v[30:33]
	v_mfma_f32_16x16x32_bf16 v[226:229], v[230:233], v[20:23], v[34:37]
	v_mfma_f32_16x16x32_bf16 v[34:37], v[210:213], v[0:3], v[178:181]
	v_mfma_f32_16x16x32_bf16 v[0:3], v[218:221], v[0:3], v[182:185]
	v_mfma_f32_16x16x32_bf16 v[74:77], v[222:225], v[4:7], v[0:3]
	v_mfma_f32_16x16x32_bf16 v[0:3], v[210:213], v[8:11], v[186:189]
	v_mfma_f32_16x16x32_bf16 v[66:69], v[214:217], v[12:15], v[0:3]
	v_mfma_f32_16x16x32_bf16 v[0:3], v[218:221], v[8:11], v[190:193]
	v_mfma_f32_16x16x32_bf16 v[58:61], v[222:225], v[12:15], v[0:3]
	v_mfma_f32_16x16x32_bf16 v[0:3], v[210:213], v[16:19], v[194:197]
	v_mfma_f32_16x16x32_bf16 v[50:53], v[214:217], v[26:29], v[0:3]
	v_mfma_f32_16x16x32_bf16 v[0:3], v[218:221], v[16:19], v[198:201]
	v_mfma_f32_16x16x32_bf16 v[42:45], v[222:225], v[26:29], v[0:3]
	v_mfma_f32_16x16x32_bf16 v[0:3], v[210:213], v[236:239], v[202:205]
	v_mfma_f32_16x16x32_bf16 v[86:89], v[214:217], v[4:7], v[34:37]
	v_mfma_f32_16x16x32_bf16 v[34:37], v[214:217], v[20:23], v[0:3]
	v_mfma_f32_16x16x32_bf16 v[0:3], v[218:221], v[236:239], v[206:209]
	v_mfma_f32_16x16x32_bf16 v[26:29], v[222:225], v[20:23], v[0:3]
	s_barrier
	s_add_u32 s85, s0, 0x200
	s_addc_u32 s96, s1, 0
	s_mov_b32 s97, 4
; #define PG8_STAGE(bufoff, gbase, voff) do { glds_s((const char*)(gbase), (voff), ldsb + (bufoff)); glds_s((const char*)(gbase) + rstep, (voff), ldsb + (bufoff) + 8192u); } while (0)
; #define PG8_LDA(dst, b, h) do { _Pragma("unroll") for (int m = 0; m < 4; ++m) _Pragma("unroll") for (int k = 0; k < 2; ++k) dst[m][k] = *(const LAS bf16x8*)(lds + PG8_SA(b, h) + aoff + m * 2048 + k * 1024); } while (0)
; #define PG8_LDB(dst, b, h) do { _Pragma("unroll") for (int n = 0; n < 2; ++n) _Pragma("unroll") for (int k = 0; k < 2; ++k) dst[n][k] = *(const LAS bf16x8*)(lds + PG8_SB(b, h) + boff + n * 2048 + k * 1024); } while (0)
; #define PG8_MMA(ai, bj, At, Bt) do { __builtin_amdgcn_s_setprio(1); _Pragma("unroll") for (int m = 0; m < 4; ++m) _Pragma("unroll") for (int n = 0; n < 2; ++n) _Pragma("unroll") for (int k = 0; k < 2; ++k) \
;         acc[ai][bj][m][n] = __builtin_amdgcn_mfma_f32_16x16x32_bf16(Bt[n][k], At[m][k], acc[ai][bj][m][n], 0, 0, 0); __builtin_amdgcn_s_setprio(0); } while (0)
; #define PG8_WAIT_V(n) asm volatile("s_waitcnt vmcnt(" #n ")" ::: "memory")
; #define PG8_WAIT_L(n) asm volatile("s_waitcnt lgkmcnt(" #n ")" ::: "memory")
; #define PG8_BAR __builtin_amdgcn_s_barrier()
; template <class Epi, class Sched>
; __device__ __forceinline__ void gemm_phase(LAS unsigned char* lds, const Gemm g, const Sched& S, const Epi& E, const int tid) {
;     ...
;         for (int t = 0; t < nt; t += 2) {
;             const bool last = (t == nt - 2);
;             const char* a1 = cA + (size_t)(t + 1) * kstep;
;             const char* a2 = last ? nA : cA + (size_t)(t + 2) * kstep; const char* b2 = last ? nB : cB + (size_t)(t + 2) * kstep;
;             const char* a3 = a2 + kstep; const char* b3 = b2 + kstep;
;             const bool relax = (t == 0) && (ui > 0);
;             PG8_LDB(B0, 0, 0); PG8_LDB(B1, 0, 1); PG8_SCHED; PG8_LDA(At, 0, 0); if (!relax) PG8_STAGE(PG8_SA(1, 1), a1 + hstep, voffA);
;             if (relax) PG8_WAIT_V(16); else PG8_WAIT_V(8);
;             PG8_WAIT_L(0); PG8_BAR; PG8_MMA(0, 0, At, B0); PG8_MMA(0, 1, At, B1); PG8_BAR; PG8_SCHED;
;             PG8_LDA(At, 0, 1); PG8_STAGE(PG8_SB(0, 0), b2, voffB); PG8_STAGE(PG8_SB(0, 1), b2 + hstep, voffB); PG8_STAGE(PG8_SA(0, 0), a2, voffA);
;             if (relax) PG8_WAIT_V(16); else PG8_WAIT_V(8);
;             PG8_WAIT_L(0); PG8_BAR; PG8_MMA(1, 0, At, B0); PG8_MMA(1, 1, At, B1); PG8_BAR; PG8_SCHED;
.LBB0_200:
	s_add_u32 s0, s2, 0x80
	s_nop 0
	ds_read_b128 v[0:3], v234
	ds_read_b128 v[4:7], v234 offset:1024
	ds_read_b128 v[8:11], v234 offset:2048
	ds_read_b128 v[12:15], v234 offset:3072
	ds_read_b128 v[16:19], v251
	ds_read_b128 v[20:23], v251 offset:1024
	ds_read_b128 v[150:153], v251 offset:2048
	ds_read_b128 v[154:157], v251 offset:3072
	s_addc_u32 s1, s3, 0
	s_cmp_eq_u32 s42, s97
	s_cselect_b32 s8, s80, s0
	s_cselect_b32 s9, s81, s1
	s_cselect_b32 s40, s82, s85
	s_cselect_b32 s41, s83, s96
	s_add_u32 s0, s8, 0x80
	s_addc_u32 s1, s9, 0
	s_add_u32 s6, s40, 0x80
	s_addc_u32 s7, s41, 0
	ds_read_b128 v[158:161], v250
	ds_read_b128 v[162:165], v250 offset:1024
	ds_read_b128 v[166:169], v250 offset:2048
	ds_read_b128 v[170:173], v250 offset:3072
	ds_read_b128 v[174:177], v250 offset:4096
	ds_read_b128 v[178:181], v250 offset:5120
	ds_read_b128 v[182:185], v250 offset:6144
	ds_read_b128 v[186:189], v250 offset:7168
	s_add_u32 s44, s2, s30
	s_addc_u32 s45, s3, s31
	s_mov_b32 m0, s65
	s_nop 0
	global_load_lds_dwordx4 v245, s[44:45]
	s_add_u32 s44, s44, s28
	s_addc_u32 s45, s45, s29
	s_mov_b32 m0, s86
	s_nop 0
	global_load_lds_dwordx4 v245, s[44:45]
	s_waitcnt vmcnt(8)
	s_waitcnt lgkmcnt(0)
	s_barrier
	v_mfma_f32_16x16x32_bf16 v[142:145], v[0:3], v[158:161], v[142:145]
	v_mfma_f32_16x16x32_bf16 v[134:137], v[8:11], v[158:161], v[134:137]
	v_mfma_f32_16x16x32_bf16 v[126:129], v[0:3], v[166:169], v[126:129]
	v_mfma_f32_16x16x32_bf16 v[118:121], v[8:11], v[166:169], v[118:121]
	v_mfma_f32_16x16x32_bf16 v[110:113], v[0:3], v[174:177], v[110:113]
	v_mfma_f32_16x16x32_bf16 v[102:105], v[8:11], v[174:177], v[102:105]
	v_mfma_f32_16x16x32_bf16 v[94:97], v[0:3], v[182:185], v[94:97]
	v_mfma_f32_16x16x32_bf16 v[82:85], v[8:11], v[182:185], v[82:85]
	v_mfma_f32_16x16x32_bf16 v[142:145], v[4:7], v[162:165], v[142:145]
	v_mfma_f32_16x16x32_bf16 v[134:137], v[12:15], v[162:165], v[134:137]
	v_mfma_f32_16x16x32_bf16 v[126:129], v[4:7], v[170:173], v[126:129]
	v_mfma_f32_16x16x32_bf16 v[118:121], v[12:15], v[170:173], v[118:121]
	v_mfma_f32_16x16x32_bf16 v[110:113], v[4:7], v[178:181], v[110:113]
	v_mfma_f32_16x16x32_bf16 v[102:105], v[12:15], v[178:181], v[102:105]
	v_mfma_f32_16x16x32_bf16 v[94:97], v[4:7], v[186:189], v[94:97]
	v_mfma_f32_16x16x32_bf16 v[82:85], v[12:15], v[186:189], v[82:85]
	v_mfma_f32_16x16x32_bf16 v[146:149], v[16:19], v[158:161], v[146:149]
	v_mfma_f32_16x16x32_bf16 v[138:141], v[150:153], v[158:161], v[138:141]
	v_mfma_f32_16x16x32_bf16 v[130:133], v[16:19], v[166:169], v[130:133]
	v_mfma_f32_16x16x32_bf16 v[122:125], v[150:153], v[166:169], v[122:125]
	v_mfma_f32_16x16x32_bf16 v[114:117], v[16:19], v[174:177], v[114:117]
	v_mfma_f32_16x16x32_bf16 v[106:109], v[150:153], v[174:177], v[106:109]
	v_mfma_f32_16x16x32_bf16 v[98:101], v[16:19], v[182:185], v[98:101]
	v_mfma_f32_16x16x32_bf16 v[90:93], v[150:153], v[182:185], v[90:93]
	v_mfma_f32_16x16x32_bf16 v[146:149], v[20:23], v[162:165], v[146:149]
	v_mfma_f32_16x16x32_bf16 v[138:141], v[154:157], v[162:165], v[138:141]
	v_mfma_f32_16x16x32_bf16 v[130:133], v[20:23], v[170:173], v[130:133]
	v_mfma_f32_16x16x32_bf16 v[122:125], v[154:157], v[170:173], v[122:125]
	v_mfma_f32_16x16x32_bf16 v[114:117], v[20:23], v[178:181], v[114:117]
	v_mfma_f32_16x16x32_bf16 v[106:109], v[154:157], v[178:181], v[106:109]
	v_mfma_f32_16x16x32_bf16 v[98:101], v[20:23], v[186:189], v[98:101]
	v_mfma_f32_16x16x32_bf16 v[90:93], v[154:157], v[186:189], v[90:93]
	s_barrier
	s_add_u32 s44, s40, s28
	ds_read_b128 v[158:161], v250 offset:16384
	ds_read_b128 v[162:165], v250 offset:17408
	ds_read_b128 v[166:169], v250 offset:18432
	ds_read_b128 v[170:173], v250 offset:19456
	ds_read_b128 v[174:177], v250 offset:20480
	ds_read_b128 v[178:181], v250 offset:21504
	ds_read_b128 v[182:185], v250 offset:22528
	ds_read_b128 v[186:189], v250 offset:23552
	s_addc_u32 s45, s41, s29
	s_mov_b32 m0, s50
	s_nop 0
	global_load_lds_dwordx4 v246, s[40:41]
	s_add_u32 s40, s40, s30
	s_mov_b32 m0, s51
	s_nop 0
	global_load_lds_dwordx4 v246, s[44:45]
	s_addc_u32 s41, s41, s31
	s_mov_b32 m0, s52
	s_nop 0
	global_load_lds_dwordx4 v246, s[40:41]
	s_add_u32 s44, s40, s28
	s_addc_u32 s45, s41, s29
	s_mov_b32 m0, s53
	s_nop 0
	global_load_lds_dwordx4 v246, s[44:45]
	s_add_u32 s44, s8, s28
	s_mov_b32 m0, s49
	s_nop 0
	global_load_lds_dwordx4 v245, s[8:9]
	s_addc_u32 s45, s9, s29
	s_mov_b32 m0, s54
	s_nop 0
	global_load_lds_dwordx4 v245, s[44:45]
	s_waitcnt vmcnt(8)
	s_waitcnt lgkmcnt(0)
	s_barrier
	v_mfma_f32_16x16x32_bf16 v[78:81], v[0:3], v[158:161], v[78:81]
	v_mfma_f32_16x16x32_bf16 v[70:73], v[8:11], v[158:161], v[70:73]
	v_mfma_f32_16x16x32_bf16 v[62:65], v[0:3], v[166:169], v[62:65]
	v_mfma_f32_16x16x32_bf16 v[54:57], v[8:11], v[166:169], v[54:57]
	v_mfma_f32_16x16x32_bf16 v[46:49], v[0:3], v[174:177], v[46:49]
	v_mfma_f32_16x16x32_bf16 v[38:41], v[8:11], v[174:177], v[38:41]
	v_mfma_f32_16x16x32_bf16 v[0:3], v[0:3], v[182:185], v[30:33]
	v_mfma_f32_16x16x32_bf16 v[78:81], v[4:7], v[162:165], v[78:81]
	v_mfma_f32_16x16x32_bf16 v[70:73], v[12:15], v[162:165], v[70:73]
	v_mfma_f32_16x16x32_bf16 v[62:65], v[4:7], v[170:173], v[62:65]
	v_mfma_f32_16x16x32_bf16 v[54:57], v[12:15], v[170:173], v[54:57]
	v_mfma_f32_16x16x32_bf16 v[46:49], v[4:7], v[178:181], v[46:49]
	v_mfma_f32_16x16x32_bf16 v[38:41], v[12:15], v[178:181], v[38:41]
	v_mfma_f32_16x16x32_bf16 v[0:3], v[4:7], v[186:189], v[0:3]
	v_mfma_f32_16x16x32_bf16 v[4:7], v[8:11], v[182:185], v[226:229]
	v_mfma_f32_16x16x32_bf16 v[4:7], v[12:15], v[186:189], v[4:7]
	v_mfma_f32_16x16x32_bf16 v[30:33], v[16:19], v[166:169], v[66:69]
	v_mfma_f32_16x16x32_bf16 v[66:69], v[20:23], v[170:173], v[30:33]
	v_mfma_f32_16x16x32_bf16 v[30:33], v[150:153], v[166:169], v[58:61]
	v_mfma_f32_16x16x32_bf16 v[58:61], v[154:157], v[170:173], v[30:33]
	v_mfma_f32_16x16x32_bf16 v[30:33], v[16:19], v[174:177], v[50:53]
	v_mfma_f32_16x16x32_bf16 v[8:11], v[16:19], v[158:161], v[86:89]
	v_mfma_f32_16x16x32_bf16 v[50:53], v[20:23], v[178:181], v[30:33]
	v_mfma_f32_16x16x32_bf16 v[30:33], v[150:153], v[174:177], v[42:45]
	v_mfma_f32_16x16x32_bf16 v[16:19], v[16:19], v[182:185], v[34:37]
	v_mfma_f32_16x16x32_bf16 v[8:11], v[20:23], v[162:165], v[8:11]
	v_mfma_f32_16x16x32_bf16 v[12:15], v[150:153], v[158:161], v[74:77]
	v_mfma_f32_16x16x32_bf16 v[42:45], v[154:157], v[178:181], v[30:33]
	v_mfma_f32_16x16x32_bf16 v[16:19], v[20:23], v[186:189], v[16:19]
	v_mfma_f32_16x16x32_bf16 v[20:23], v[150:153], v[182:185], v[26:29]
	v_mfma_f32_16x16x32_bf16 v[12:15], v[154:157], v[162:165], v[12:15]
	v_mfma_f32_16x16x32_bf16 v[20:23], v[154:157], v[186:189], v[20:23]
	s_barrier
; #define PG8_STAGE(bufoff, gbase, voff) do { glds_s((const char*)(gbase), (voff), ldsb + (bufoff)); glds_s((const char*)(gbase) + rstep, (voff), ldsb + (bufoff) + 8192u); } while (0)
; #define PG8_LDA(dst, b, h) do { _Pragma("unroll") for (int m = 0; m < 4; ++m) _Pragma("unroll") for (int k = 0; k < 2; ++k) dst[m][k] = *(const LAS bf16x8*)(lds + PG8_SA(b, h) + aoff + m * 2048 + k * 1024); } while (0)
; #define PG8_LDB(dst, b, h) do { _Pragma("unroll") for (int n = 0; n < 2; ++n) _Pragma("unroll") for (int k = 0; k < 2; ++k) dst[n][k] = *(const LAS bf16x8*)(lds + PG8_SB(b, h) + boff + n * 2048 + k * 1024); } while (0)
; #define PG8_MMA(ai, bj, At, Bt) do { __builtin_amdgcn_s_setprio(1); _Pragma("unroll") for (int m = 0; m < 4; ++m) _Pragma("unroll") for (int n = 0; n < 2; ++n) _Pragma("unroll") for (int k = 0; k < 2; ++k) \
;         acc[ai][bj][m][n] = __builtin_amdgcn_mfma_f32_16x16x32_bf16(Bt[n][k], At[m][k], acc[ai][bj][m][n], 0, 0, 0); __builtin_amdgcn_s_setprio(0); } while (0)
; #define PG8_WAIT_V(n) asm volatile("s_waitcnt vmcnt(" #n ")" ::: "memory")
; #define PG8_WAIT_L(n) asm volatile("s_waitcnt lgkmcnt(" #n ")" ::: "memory")
; #define PG8_BAR __builtin_amdgcn_s_barrier()
; #define PG8_SCHED __builtin_amdgcn_sched_barrier(0)
; template <class Epi, class Sched>
; __device__ __forceinline__ void gemm_phase(LAS unsigned char* lds, const Gemm g, const Sched& S, const Epi& E, const int tid) {
;     ...
;             PG8_LDB(B0, 1, 0); PG8_LDB(B1, 1, 1); PG8_SCHED; PG8_LDA(At, 1, 0); PG8_STAGE(PG8_SA(0, 1), a2 + hstep, voffA);
;             if (relax) PG8_WAIT_V(16); else PG8_WAIT_V(8);
;             PG8_WAIT_L(0); PG8_BAR; PG8_MMA(0, 0, At, B0); PG8_MMA(0, 1, At, B1); PG8_BAR; PG8_SCHED;
;             PG8_LDA(At, 1, 1); PG8_STAGE(PG8_SB(1, 0), b3, voffB); PG8_STAGE(PG8_SB(1, 1), b3 + hstep, voffB); PG8_STAGE(PG8_SA(1, 0), a3, voffA);
;             PG8_WAIT_V(8); PG8_WAIT_L(0); PG8_BAR; PG8_MMA(1, 0, At, B0); PG8_MMA(1, 1, At, B1); PG8_BAR; PG8_SCHED;
;         }
;         if (wr == 0) PG8_BAR;
	ds_read_b128 v[24:27], v252
	ds_read_b128 v[28:31], v252 offset:1024
	ds_read_b128 v[34:37], v252 offset:2048
	ds_read_b128 v[74:77], v252 offset:3072
	ds_read_b128 v[150:153], v240
	ds_read_b128 v[154:157], v240 offset:1024
	ds_read_b128 v[158:161], v240 offset:2048
	ds_read_b128 v[162:165], v240 offset:3072
	ds_read_b128 v[86:89], v250 offset:32768
	ds_read_b128 v[166:169], v250 offset:33792
	ds_read_b128 v[170:173], v250 offset:34816
	ds_read_b128 v[174:177], v250 offset:35840
	ds_read_b128 v[178:181], v250 offset:36864
	ds_read_b128 v[182:185], v250 offset:37888
	ds_read_b128 v[186:189], v250 offset:38912
	ds_read_b128 v[190:193], v250 offset:39936
	s_add_u32 s8, s8, s30
	s_addc_u32 s9, s9, s31
	s_mov_b32 m0, s55
	s_nop 0
	global_load_lds_dwordx4 v245, s[8:9]
	s_add_u32 s8, s8, s28
	s_addc_u32 s9, s9, s29
	s_mov_b32 m0, s56
	s_nop 0
	global_load_lds_dwordx4 v245, s[8:9]
	s_waitcnt vmcnt(8)
	s_waitcnt lgkmcnt(0)
	s_barrier
	v_mfma_f32_16x16x32_bf16 v[142:145], v[24:27], v[86:89], v[142:145]
	v_mfma_f32_16x16x32_bf16 v[134:137], v[34:37], v[86:89], v[134:137]
	v_mfma_f32_16x16x32_bf16 v[126:129], v[24:27], v[170:173], v[126:129]
	v_mfma_f32_16x16x32_bf16 v[118:121], v[34:37], v[170:173], v[118:121]
	v_mfma_f32_16x16x32_bf16 v[110:113], v[24:27], v[178:181], v[110:113]
	v_mfma_f32_16x16x32_bf16 v[102:105], v[34:37], v[178:181], v[102:105]
	v_mfma_f32_16x16x32_bf16 v[94:97], v[24:27], v[186:189], v[94:97]
	v_mfma_f32_16x16x32_bf16 v[82:85], v[34:37], v[186:189], v[82:85]
	v_mfma_f32_16x16x32_bf16 v[142:145], v[28:31], v[166:169], v[142:145]
	v_mfma_f32_16x16x32_bf16 v[134:137], v[74:77], v[166:169], v[134:137]
	v_mfma_f32_16x16x32_bf16 v[126:129], v[28:31], v[174:177], v[126:129]
	v_mfma_f32_16x16x32_bf16 v[118:121], v[74:77], v[174:177], v[118:121]
	v_mfma_f32_16x16x32_bf16 v[110:113], v[28:31], v[182:185], v[110:113]
	v_mfma_f32_16x16x32_bf16 v[102:105], v[74:77], v[182:185], v[102:105]
	v_mfma_f32_16x16x32_bf16 v[94:97], v[28:31], v[190:193], v[94:97]
	v_mfma_f32_16x16x32_bf16 v[82:85], v[74:77], v[190:193], v[82:85]
	v_mfma_f32_16x16x32_bf16 v[146:149], v[150:153], v[86:89], v[146:149]
	v_mfma_f32_16x16x32_bf16 v[86:89], v[158:161], v[86:89], v[138:141]
	v_mfma_f32_16x16x32_bf16 v[138:141], v[162:165], v[166:169], v[86:89]
	v_mfma_f32_16x16x32_bf16 v[86:89], v[150:153], v[170:173], v[130:133]
	v_mfma_f32_16x16x32_bf16 v[130:133], v[154:157], v[174:177], v[86:89]
	v_mfma_f32_16x16x32_bf16 v[86:89], v[158:161], v[170:173], v[122:125]
	v_mfma_f32_16x16x32_bf16 v[122:125], v[162:165], v[174:177], v[86:89]
	v_mfma_f32_16x16x32_bf16 v[86:89], v[150:153], v[178:181], v[114:117]
	v_mfma_f32_16x16x32_bf16 v[114:117], v[154:157], v[182:185], v[86:89]
	v_mfma_f32_16x16x32_bf16 v[86:89], v[158:161], v[178:181], v[106:109]
	v_mfma_f32_16x16x32_bf16 v[106:109], v[162:165], v[182:185], v[86:89]
	v_mfma_f32_16x16x32_bf16 v[86:89], v[150:153], v[186:189], v[98:101]
	v_mfma_f32_16x16x32_bf16 v[98:101], v[154:157], v[190:193], v[86:89]
	v_mfma_f32_16x16x32_bf16 v[86:89], v[158:161], v[186:189], v[90:93]
	v_mfma_f32_16x16x32_bf16 v[146:149], v[154:157], v[166:169], v[146:149]
	v_mfma_f32_16x16x32_bf16 v[90:93], v[162:165], v[190:193], v[86:89]
	s_barrier
	ds_read_b128 v[166:169], v250 offset:49152
	ds_read_b128 v[170:173], v250 offset:50176
	ds_read_b128 v[174:177], v250 offset:51200
	ds_read_b128 v[178:181], v250 offset:52224
	ds_read_b128 v[182:185], v250 offset:53248
	ds_read_b128 v[186:189], v250 offset:54272
	ds_read_b128 v[190:193], v250 offset:55296
	ds_read_b128 v[194:197], v250 offset:56320
	s_mov_b32 m0, s59
	s_nop 0
	global_load_lds_dwordx4 v246, s[6:7]
	s_add_u32 s6, s6, s28
	s_addc_u32 s7, s7, s29
	s_mov_b32 m0, s60
	s_nop 0
	global_load_lds_dwordx4 v246, s[6:7]
	s_add_u32 s6, s40, 0x80
	s_addc_u32 s7, s41, 0
	s_mov_b32 m0, s63
	s_nop 0
	global_load_lds_dwordx4 v246, s[6:7]
	s_add_u32 s6, s6, s28
	s_addc_u32 s7, s7, s29
	s_mov_b32 m0, s64
	s_nop 0
	global_load_lds_dwordx4 v246, s[6:7]
	s_mov_b32 m0, s61
	s_nop 0
	global_load_lds_dwordx4 v245, s[0:1]
	s_add_u32 s0, s0, s28
	s_addc_u32 s1, s1, s29
	s_mov_b32 m0, s62
	s_nop 0
	global_load_lds_dwordx4 v245, s[0:1]
	s_waitcnt vmcnt(8)
	s_waitcnt lgkmcnt(0)
	s_barrier
	v_mfma_f32_16x16x32_bf16 v[78:81], v[24:27], v[166:169], v[78:81]
	v_mfma_f32_16x16x32_bf16 v[62:65], v[24:27], v[174:177], v[62:65]
	v_mfma_f32_16x16x32_bf16 v[46:49], v[24:27], v[182:185], v[46:49]
	v_mfma_f32_16x16x32_bf16 v[0:3], v[24:27], v[190:193], v[0:3]
	v_mfma_f32_16x16x32_bf16 v[78:81], v[28:31], v[170:173], v[78:81]
	v_mfma_f32_16x16x32_bf16 v[70:73], v[34:37], v[166:169], v[70:73]
	v_mfma_f32_16x16x32_bf16 v[62:65], v[28:31], v[178:181], v[62:65]
	v_mfma_f32_16x16x32_bf16 v[54:57], v[34:37], v[174:177], v[54:57]
	v_mfma_f32_16x16x32_bf16 v[46:49], v[28:31], v[186:189], v[46:49]
	v_mfma_f32_16x16x32_bf16 v[38:41], v[34:37], v[182:185], v[38:41]
	v_mfma_f32_16x16x32_bf16 v[30:33], v[28:31], v[194:197], v[0:3]
	v_mfma_f32_16x16x32_bf16 v[0:3], v[34:37], v[190:193], v[4:7]
	v_mfma_f32_16x16x32_bf16 v[70:73], v[74:77], v[170:173], v[70:73]
	v_mfma_f32_16x16x32_bf16 v[54:57], v[74:77], v[178:181], v[54:57]
	v_mfma_f32_16x16x32_bf16 v[38:41], v[74:77], v[186:189], v[38:41]
	v_mfma_f32_16x16x32_bf16 v[226:229], v[74:77], v[194:197], v[0:3]
	v_mfma_f32_16x16x32_bf16 v[0:3], v[150:153], v[166:169], v[8:11]
	v_mfma_f32_16x16x32_bf16 v[86:89], v[154:157], v[170:173], v[0:3]
	v_mfma_f32_16x16x32_bf16 v[0:3], v[158:161], v[166:169], v[12:15]
	v_mfma_f32_16x16x32_bf16 v[74:77], v[162:165], v[170:173], v[0:3]
	v_mfma_f32_16x16x32_bf16 v[0:3], v[150:153], v[174:177], v[66:69]
	v_mfma_f32_16x16x32_bf16 v[66:69], v[154:157], v[178:181], v[0:3]
	v_mfma_f32_16x16x32_bf16 v[0:3], v[158:161], v[174:177], v[58:61]
	v_mfma_f32_16x16x32_bf16 v[58:61], v[162:165], v[178:181], v[0:3]
	v_mfma_f32_16x16x32_bf16 v[0:3], v[150:153], v[182:185], v[50:53]
	v_mfma_f32_16x16x32_bf16 v[50:53], v[154:157], v[186:189], v[0:3]
	v_mfma_f32_16x16x32_bf16 v[0:3], v[158:161], v[182:185], v[42:45]
	v_mfma_f32_16x16x32_bf16 v[42:45], v[162:165], v[186:189], v[0:3]
	v_mfma_f32_16x16x32_bf16 v[0:3], v[150:153], v[190:193], v[16:19]
	v_mfma_f32_16x16x32_bf16 v[34:37], v[154:157], v[194:197], v[0:3]
	v_mfma_f32_16x16x32_bf16 v[0:3], v[158:161], v[190:193], v[20:23]
	v_mfma_f32_16x16x32_bf16 v[26:29], v[162:165], v[194:197], v[0:3]
	s_barrier
	s_add_u32 s2, s2, 0x100
	s_addc_u32 s3, s3, 0
	s_add_i32 s0, s97, 2
	s_add_u32 s85, s85, 0x100
	s_addc_u32 s96, s96, 0
	s_cmp_ge_u32 s97, s42
	s_mov_b32 s97, s0
	s_cbranch_scc0 .LBB0_200
	s_and_b64 vcc, exec, s[68:69]
	s_cbranch_vccz .LBB0_203
	s_barrier
